# v29 + LRU pass-2 carry-in chain: the up-to-3 AGGW rows are read from LDS in one batch (one wait) instead of serial read-wait-fma hops; generic loop kept as fallback
# baseline (speedup 1.0000x reference)
.LBB0_779:
	s_cmp_gt_u32 s3, 3
	s_cbranch_scc1 .Lmy_hin_g0
	ds_read_b64 v[100:101], v20
	ds_read_b64 v[102:103], v20 offset:512
	ds_read_b64 v[20:21], v20 offset:1024
	s_waitcnt lgkmcnt(0)
	v_fma_f32 v23, v23, v100, v101
	s_cmp_lt_u32 s3, 2
	s_cbranch_scc1 .LBB0_780
	v_fma_f32 v23, v23, v102, v103
	s_cmp_lt_u32 s3, 3
	s_cbranch_scc1 .LBB0_780
	v_fma_f32 v23, v23, v20, v21
	s_branch .LBB0_780

.LBB0_790:
	s_cmp_gt_u32 s9, 3
	s_cbranch_scc1 .Lmy_hin_g1
	ds_read_b64 v[112:113], v20
	ds_read_b64 v[114:115], v20 offset:512
	ds_read_b64 v[20:21], v20 offset:1024
	s_waitcnt lgkmcnt(0)
	v_fma_f32 v23, v23, v112, v113
	s_cmp_lt_u32 s9, 2
	s_cbranch_scc1 .LBB0_791
	v_fma_f32 v23, v23, v114, v115
	s_cmp_lt_u32 s9, 3
	s_cbranch_scc1 .LBB0_791
	v_fma_f32 v23, v23, v20, v21
	s_branch .LBB0_791

.LBB0_801:
	s_cmp_gt_u32 s9, 3
	s_cbranch_scc1 .Lmy_hin_g2
	ds_read_b64 v[110:111], v20
	ds_read_b64 v[112:113], v20 offset:512
	ds_read_b64 v[20:21], v20 offset:1024
	s_waitcnt lgkmcnt(0)
	v_fma_f32 v23, v23, v110, v111
	s_cmp_lt_u32 s9, 2
	s_cbranch_scc1 .LBB0_802
	v_fma_f32 v23, v23, v112, v113
	s_cmp_lt_u32 s9, 3
	s_cbranch_scc1 .LBB0_802
	v_fma_f32 v23, v23, v20, v21
	s_branch .LBB0_802

.LBB0_812:
	s_cmp_gt_u32 s9, 3
	s_cbranch_scc1 .Lmy_hin_g3
	ds_read_b64 v[104:105], v20
	ds_read_b64 v[106:107], v20 offset:512
	ds_read_b64 v[20:21], v20 offset:1024
	s_waitcnt lgkmcnt(0)
	v_fma_f32 v23, v23, v104, v105
	s_cmp_lt_u32 s9, 2
	s_cbranch_scc1 .LBB0_813
	v_fma_f32 v23, v23, v106, v107
	s_cmp_lt_u32 s9, 3
	s_cbranch_scc1 .LBB0_813
	v_fma_f32 v23, v23, v20, v21
	s_branch .LBB0_813

.LBB0_845:
	s_cmp_gt_u32 s9, 3
	s_cbranch_scc1 .Lmy_hin_g6
	ds_read_b64 v[96:97], v20
	ds_read_b64 v[98:99], v20 offset:512
	ds_read_b64 v[20:21], v20 offset:1024
	s_waitcnt lgkmcnt(0)
	v_fma_f32 v23, v23, v96, v97
	s_cmp_lt_u32 s9, 2
	s_cbranch_scc1 .LBB0_846
	v_fma_f32 v23, v23, v98, v99
	s_cmp_lt_u32 s9, 3
	s_cbranch_scc1 .LBB0_846
	v_fma_f32 v23, v23, v20, v21
	s_branch .LBB0_846

.LBB0_856:
	s_cmp_gt_u32 s9, 3
	s_cbranch_scc1 .Lmy_hin_g7
	ds_read_b64 v[66:67], v8
	ds_read_b64 v[74:75], v8 offset:512
	ds_read_b64 v[8:9], v8 offset:1024
	s_waitcnt lgkmcnt(0)
	v_fma_f32 v11, v11, v66, v67
	s_cmp_lt_u32 s9, 2
	s_cbranch_scc1 .LBB0_857
	v_fma_f32 v11, v11, v74, v75
	s_cmp_lt_u32 s9, 3
	s_cbranch_scc1 .LBB0_857
	v_fma_f32 v11, v11, v8, v9
	s_branch .LBB0_857
